# final RMSNorm row loop double-buffered (next row's loads in flight, counted vmcnt) + its xor16/xor32 shuffles via permlane swaps
# baseline (speedup 1.0000x reference)
; __device__ __forceinline__ float bflo(unsigned u) { return __uint_as_float(u << 16); }
; __device__ __forceinline__ float bfhi(unsigned u) { return __uint_as_float(u & 0xffff0000u); }
; __global__ void __launch_bounds__(512, 2) mk_fwd(Args a) {
;     ...
;             for (int row = gw; row < T; row += NGW) {
;                 f32x4* xr = (f32x4*)(X + (size_t)row * DM) + lane; const u32x2* xb = (const u32x2*)(HB + (size_t)row * DM) + lane; f32x4 v[4]; float s = 0.f;
; #pragma unroll
;                 for (int j = 0; j < 4; ++j) { const u32x2 w = xb[64 * j]; v[j] = (f32x4){bflo(w.x), bfhi(w.x), bflo(w.y), bfhi(w.y)}; s += (v[j].x * v[j].x + v[j].y * v[j].y) + (v[j].z * v[j].z + v[j].w * v[j].w); }
;                 const float rs = rsqrtf(wave_sum(s) * (1.0f / DM) + EPS);
; #pragma unroll
;                 for (int j = 0; j < 4; ++j) { const f32x4 g4 = ((const f32x4*)gf)[lane + 64 * j]; xr[64 * j] = v[j] * rs * g4; }
;             }
.LBB0_25:
	s_and_b64 vcc, exec, s[6:7]
	s_cbranch_vccz .LBB0_30
	v_readlane_b32 s6, v254, 1
	v_readlane_b32 s8, v254, 3
	s_cmpk_gt_i32 s2, 0x7fff
	v_readlane_b32 s7, v254, 2
	v_readlane_b32 s9, v254, 4
	s_cbranch_scc1 .LBB0_29
	v_and_b32_e32 v0, 64, v217
	v_add_u32_e32 v0, 64, v0
	s_waitcnt lgkmcnt(0)
	v_xor_b32_e32 v2, 1, v217
	v_cmp_lt_i32_e32 vcc, v2, v0
	v_readlane_b32 s4, v254, 40
	v_readlane_b32 s5, v254, 41
	v_cndmask_b32_e32 v2, v217, v2, vcc
	v_lshlrev_b32_e32 v8, 2, v2
	v_xor_b32_e32 v2, 2, v217
	v_cmp_lt_i32_e32 vcc, v2, v0
	s_load_dwordx2 s[4:5], s[4:5], 0xa0
	v_and_b32_e32 v4, 63, v230
	v_cndmask_b32_e32 v2, v217, v2, vcc
	v_lshlrev_b32_e32 v9, 2, v2
	v_xor_b32_e32 v2, 4, v217
	v_cmp_lt_i32_e32 vcc, v2, v0
	s_ashr_i32 s3, s2, 31
	v_readlane_b32 s10, v254, 44
	v_cndmask_b32_e32 v2, v217, v2, vcc
	v_lshlrev_b32_e32 v10, 2, v2
	v_xor_b32_e32 v2, 8, v217
	v_cmp_lt_i32_e32 vcc, v2, v0
	v_readlane_b32 s11, v254, 45
	v_mov_b32_e32 v5, v1
	v_cndmask_b32_e32 v2, v217, v2, vcc
	v_lshlrev_b32_e32 v11, 2, v2
	v_xor_b32_e32 v2, 16, v217
	v_cmp_lt_i32_e32 vcc, v2, v0
	s_nop 1
	v_cndmask_b32_e32 v2, v217, v2, vcc
	v_lshlrev_b32_e32 v12, 2, v2
	v_xor_b32_e32 v2, 32, v217
	v_cmp_lt_i32_e32 vcc, v2, v0
	s_nop 1
	v_cndmask_b32_e32 v0, v217, v2, vcc
	v_lshlrev_b32_e32 v13, 2, v0
	v_lshlrev_b32_e32 v0, 4, v4
	s_waitcnt lgkmcnt(0)
	v_lshl_add_u64 v[2:3], s[4:5], 0, v[0:1]
	s_lshl_b64 s[4:5], s[2:3], 11
	s_add_u32 s4, s10, s4
	v_lshlrev_b32_e32 v4, 3, v4
	s_addc_u32 s5, s11, s5
	v_lshl_add_u64 v[4:5], s[4:5], 0, v[4:5]
	s_lshl_b64 s[4:5], s[2:3], 12
	s_add_u32 s4, s36, s4
	s_addc_u32 s5, s37, s5
	v_lshl_add_u64 v[6:7], s[4:5], 0, v[0:1]
	global_load_dwordx4 v[52:55], v[2:3], off
	global_load_dwordx4 v[56:59], v[2:3], off offset:1024
	global_load_dwordx4 v[60:63], v[2:3], off offset:2048
	global_load_dwordx4 v[64:67], v[2:3], off offset:3072
	global_load_dwordx2 v[18:19], v[4:5], off
	global_load_dwordx2 v[20:21], v[4:5], off offset:512
	global_load_dwordx2 v[22:23], v[4:5], off offset:1024
	global_load_dwordx2 v[24:25], v[4:5], off offset:1536
	v_lshl_add_u64 v[4:5], v[4:5], 0, s[8:9]
.LBB0_28:
	s_add_i32 s2, s2, s96
	s_cmpk_gt_i32 s2, 0x7fff
	s_cbranch_scc1 .Lfn_a_last
	global_load_dwordx2 v[68:69], v[4:5], off
	global_load_dwordx2 v[70:71], v[4:5], off offset:512
	global_load_dwordx2 v[72:73], v[4:5], off offset:1024
	global_load_dwordx2 v[74:75], v[4:5], off offset:1536
	v_lshl_add_u64 v[4:5], v[4:5], 0, s[8:9]
	s_waitcnt vmcnt(4) lgkmcnt(0)
	s_branch .Lfn_a_go
.Lfn_a_last:
	s_waitcnt vmcnt(0) lgkmcnt(0)
.Lfn_a_go:
	v_lshlrev_b32_e32 v26, 16, v18
	v_and_b32_e32 v27, 0xffff0000, v18
	v_lshlrev_b32_e32 v18, 16, v19
	v_and_b32_e32 v19, 0xffff0000, v19
	v_lshlrev_b32_e32 v29, 16, v21
	v_lshlrev_b32_e32 v28, 16, v20
	v_and_b32_e32 v21, 0xffff0000, v21
	v_and_b32_e32 v20, 0xffff0000, v20
	v_lshlrev_b32_e32 v30, 16, v22
	v_and_b32_e32 v31, 0xffff0000, v22
	v_lshlrev_b32_e32 v22, 16, v23
	v_and_b32_e32 v23, 0xffff0000, v23
	v_lshlrev_b32_e32 v33, 16, v24
	v_mul_f32_e32 v0, v19, v19
	v_mul_f32_e32 v32, v27, v27
	v_pk_mul_f32 v[36:37], v[20:21], v[20:21]
	v_mov_b32_e32 v39, v33
	v_mul_f32_e32 v38, v23, v23
	v_pk_fma_f32 v[40:41], v[18:19], v[18:19], v[0:1] op_sel_hi:[1,1,0]
	v_pk_fma_f32 v[42:43], v[26:27], v[26:27], v[32:33] op_sel_hi:[1,1,0]
	v_and_b32_e32 v35, 0xffff0000, v24
	v_lshlrev_b32_e32 v24, 16, v25
	v_and_b32_e32 v25, 0xffff0000, v25
	v_mul_f32_e32 v34, v31, v31
	v_pk_fma_f32 v[36:37], v[28:29], v[28:29], v[36:37]
	v_pk_fma_f32 v[46:47], v[22:23], v[22:23], v[38:39] op_sel_hi:[1,1,0]
	v_mov_b32_e32 v32, v42
	v_mov_b32_e32 v38, v40
	v_mul_f32_e32 v48, v35, v35
	v_mul_f32_e32 v49, v24, v24
	v_mul_f32_e32 v50, v25, v25
	v_pk_fma_f32 v[44:45], v[30:31], v[30:31], v[34:35] op_sel_hi:[1,1,0]
	v_pk_add_f32 v[40:41], v[42:43], v[40:41]
	v_pk_add_f32 v[36:37], v[36:37], v[36:37] op_sel:[0,1] op_sel_hi:[1,0]
	v_pk_mul_f32 v[38:39], v[32:33], v[38:39]
	v_mov_b32_e32 v45, v49
	v_mov_b32_e32 v47, v50
	v_mov_b32_e32 v37, v48
	v_mov_b32_e32 v41, v39
	v_pk_add_f32 v[42:43], v[44:45], v[46:47]
	v_pk_add_f32 v[36:37], v[40:41], v[36:37]
	v_mov_b32_e32 v34, v33
	v_pk_add_f32 v[36:37], v[36:37], v[42:43]
	s_nop 0
	v_add_f32_e32 v0, v36, v37
	ds_bpermute_b32 v32, v8, v0
	s_waitcnt lgkmcnt(0)
	v_add_f32_e32 v0, v0, v32
	ds_bpermute_b32 v32, v9, v0
	s_waitcnt lgkmcnt(0)
	v_add_f32_e32 v0, v0, v32
	ds_bpermute_b32 v32, v10, v0
	s_waitcnt lgkmcnt(0)
	v_add_f32_e32 v0, v0, v32
	ds_bpermute_b32 v32, v11, v0
	s_waitcnt lgkmcnt(0)
	v_add_f32_e32 v0, v0, v32
	v_mov_b32_e32 v32, v0
	s_nop 1
	v_permlane16_swap_b32_e32 v32, v0
	v_add_f32_e32 v0, v0, v32
	v_mov_b32_e32 v32, v0
	s_nop 1
	v_permlane32_swap_b32_e32 v32, v0
	v_add_f32_e32 v0, v0, v32
	v_fmamk_f32 v0, v0, 0x3a800000, v205
	v_mul_f32_e32 v32, 0x4b800000, v0
	v_cmp_gt_f32_e32 vcc, s77, v0
	s_nop 1
	v_cndmask_b32_e32 v0, v0, v32, vcc
	v_rsq_f32_e32 v0, v0
	s_nop 0
	v_mul_f32_e32 v32, 0x45800000, v0
	v_cndmask_b32_e32 v0, v0, v32, vcc
	v_pk_mul_f32 v[26:27], v[0:1], v[26:27] op_sel_hi:[0,1]
	v_pk_mul_f32 v[18:19], v[0:1], v[18:19] op_sel_hi:[0,1]
	v_pk_mul_f32 v[16:17], v[18:19], v[54:55]
	v_pk_mul_f32 v[14:15], v[26:27], v[52:53]
	flat_store_dwordx4 v[6:7], v[14:17]
	v_mov_b32_e32 v18, v29
	v_mov_b32_e32 v19, v21
	v_mov_b32_e32 v29, v20
	v_pk_mul_f32 v[18:19], v[0:1], v[18:19] op_sel_hi:[0,1]
	v_pk_mul_f32 v[20:21], v[0:1], v[28:29] op_sel_hi:[0,1]
	v_pk_mul_f32 v[14:15], v[20:21], v[56:57]
	v_pk_mul_f32 v[16:17], v[18:19], v[58:59]
	flat_store_dwordx4 v[6:7], v[14:17] offset:1024
	v_pk_mul_f32 v[18:19], v[0:1], v[22:23] op_sel_hi:[0,1]
	v_pk_mul_f32 v[20:21], v[0:1], v[30:31] op_sel_hi:[0,1]
	v_pk_mul_f32 v[14:15], v[20:21], v[60:61]
	v_pk_mul_f32 v[16:17], v[18:19], v[62:63]
	flat_store_dwordx4 v[6:7], v[14:17] offset:2048
	v_pk_mul_f32 v[18:19], v[0:1], v[24:25] op_sel_hi:[0,1]
	v_pk_mul_f32 v[20:21], v[0:1], v[34:35] op_sel_hi:[0,1]
	v_pk_mul_f32 v[14:15], v[20:21], v[64:65]
	v_pk_mul_f32 v[16:17], v[18:19], v[66:67]
	flat_store_dwordx4 v[6:7], v[14:17] offset:3072
	v_lshl_add_u64 v[6:7], v[6:7], 0, s[6:7]
	s_cmpk_gt_i32 s2, 0x7fff
	s_cbranch_scc1 .LBB0_29
	s_add_i32 s2, s2, s96
	s_cmpk_gt_i32 s2, 0x7fff
	s_cbranch_scc1 .Lfn_b_last
	global_load_dwordx2 v[18:19], v[4:5], off
	global_load_dwordx2 v[20:21], v[4:5], off offset:512
	global_load_dwordx2 v[22:23], v[4:5], off offset:1024
	global_load_dwordx2 v[24:25], v[4:5], off offset:1536
	v_lshl_add_u64 v[4:5], v[4:5], 0, s[8:9]
	s_waitcnt vmcnt(4) lgkmcnt(0)
	s_branch .Lfn_b_go

; __device__ __forceinline__ float bflo(unsigned u) { return __uint_as_float(u << 16); }
; __device__ __forceinline__ float bfhi(unsigned u) { return __uint_as_float(u & 0xffff0000u); }
; __global__ void __launch_bounds__(512, 2) mk_fwd(Args a) {
;     ...
;             for (int row = gw; row < T; row += NGW) {
;                 f32x4* xr = (f32x4*)(X + (size_t)row * DM) + lane; const u32x2* xb = (const u32x2*)(HB + (size_t)row * DM) + lane; f32x4 v[4]; float s = 0.f;
; #pragma unroll
;                 for (int j = 0; j < 4; ++j) { const u32x2 w = xb[64 * j]; v[j] = (f32x4){bflo(w.x), bfhi(w.x), bflo(w.y), bfhi(w.y)}; s += (v[j].x * v[j].x + v[j].y * v[j].y) + (v[j].z * v[j].z + v[j].w * v[j].w); }
;                 const float rs = rsqrtf(wave_sum(s) * (1.0f / DM) + EPS);
; #pragma unroll
;                 for (int j = 0; j < 4; ++j) { const f32x4 g4 = ((const f32x4*)gf)[lane + 64 * j]; xr[64 * j] = v[j] * rs * g4; }
;             }
.Lfn_b_go:
	v_lshlrev_b32_e32 v26, 16, v68
	v_and_b32_e32 v27, 0xffff0000, v68
	v_lshlrev_b32_e32 v68, 16, v69
	v_and_b32_e32 v69, 0xffff0000, v69
	v_lshlrev_b32_e32 v29, 16, v71
	v_lshlrev_b32_e32 v28, 16, v70
	v_and_b32_e32 v71, 0xffff0000, v71
	v_and_b32_e32 v70, 0xffff0000, v70
	v_lshlrev_b32_e32 v30, 16, v72
	v_and_b32_e32 v31, 0xffff0000, v72
	v_lshlrev_b32_e32 v72, 16, v73
	v_and_b32_e32 v73, 0xffff0000, v73
	v_lshlrev_b32_e32 v33, 16, v74
	v_mul_f32_e32 v0, v69, v69
	v_mul_f32_e32 v32, v27, v27
	v_pk_mul_f32 v[36:37], v[70:71], v[70:71]
	v_mov_b32_e32 v39, v33
	v_mul_f32_e32 v38, v73, v73
	v_pk_fma_f32 v[40:41], v[68:69], v[68:69], v[0:1] op_sel_hi:[1,1,0]
	v_pk_fma_f32 v[42:43], v[26:27], v[26:27], v[32:33] op_sel_hi:[1,1,0]
	v_and_b32_e32 v35, 0xffff0000, v74
	v_lshlrev_b32_e32 v74, 16, v75
	v_and_b32_e32 v75, 0xffff0000, v75
	v_mul_f32_e32 v34, v31, v31
	v_pk_fma_f32 v[36:37], v[28:29], v[28:29], v[36:37]
	v_pk_fma_f32 v[46:47], v[72:73], v[72:73], v[38:39] op_sel_hi:[1,1,0]
	v_mov_b32_e32 v32, v42
	v_mov_b32_e32 v38, v40
	v_mul_f32_e32 v48, v35, v35
	v_mul_f32_e32 v49, v74, v74
	v_mul_f32_e32 v50, v75, v75
	v_pk_fma_f32 v[44:45], v[30:31], v[30:31], v[34:35] op_sel_hi:[1,1,0]
	v_pk_add_f32 v[40:41], v[42:43], v[40:41]
	v_pk_add_f32 v[36:37], v[36:37], v[36:37] op_sel:[0,1] op_sel_hi:[1,0]
	v_pk_mul_f32 v[38:39], v[32:33], v[38:39]
	v_mov_b32_e32 v45, v49
	v_mov_b32_e32 v47, v50
	v_mov_b32_e32 v37, v48
	v_mov_b32_e32 v41, v39
	v_pk_add_f32 v[42:43], v[44:45], v[46:47]
	v_pk_add_f32 v[36:37], v[40:41], v[36:37]
	v_mov_b32_e32 v34, v33
	v_pk_add_f32 v[36:37], v[36:37], v[42:43]
	s_nop 0
	v_add_f32_e32 v0, v36, v37
	ds_bpermute_b32 v32, v8, v0
	s_waitcnt lgkmcnt(0)
	v_add_f32_e32 v0, v0, v32
	ds_bpermute_b32 v32, v9, v0
	s_waitcnt lgkmcnt(0)
	v_add_f32_e32 v0, v0, v32
	ds_bpermute_b32 v32, v10, v0
	s_waitcnt lgkmcnt(0)
	v_add_f32_e32 v0, v0, v32
	ds_bpermute_b32 v32, v11, v0
	s_waitcnt lgkmcnt(0)
	v_add_f32_e32 v0, v0, v32
	v_mov_b32_e32 v32, v0
	s_nop 1
	v_permlane16_swap_b32_e32 v32, v0
	v_add_f32_e32 v0, v0, v32
	v_mov_b32_e32 v32, v0
	s_nop 1
	v_permlane32_swap_b32_e32 v32, v0
	v_add_f32_e32 v0, v0, v32
	v_fmamk_f32 v0, v0, 0x3a800000, v205
	v_mul_f32_e32 v32, 0x4b800000, v0
	v_cmp_gt_f32_e32 vcc, s77, v0
	s_nop 1
	v_cndmask_b32_e32 v0, v0, v32, vcc
	v_rsq_f32_e32 v0, v0
	s_nop 0
	v_mul_f32_e32 v32, 0x45800000, v0
	v_cndmask_b32_e32 v0, v0, v32, vcc
	v_pk_mul_f32 v[26:27], v[0:1], v[26:27] op_sel_hi:[0,1]
	v_pk_mul_f32 v[68:69], v[0:1], v[68:69] op_sel_hi:[0,1]
	v_pk_mul_f32 v[16:17], v[68:69], v[54:55]
	v_pk_mul_f32 v[14:15], v[26:27], v[52:53]
	flat_store_dwordx4 v[6:7], v[14:17]
	v_mov_b32_e32 v68, v29
	v_mov_b32_e32 v69, v71
	v_mov_b32_e32 v29, v70
	v_pk_mul_f32 v[68:69], v[0:1], v[68:69] op_sel_hi:[0,1]
	v_pk_mul_f32 v[70:71], v[0:1], v[28:29] op_sel_hi:[0,1]
	v_pk_mul_f32 v[14:15], v[70:71], v[56:57]
	v_pk_mul_f32 v[16:17], v[68:69], v[58:59]
	flat_store_dwordx4 v[6:7], v[14:17] offset:1024
	v_pk_mul_f32 v[68:69], v[0:1], v[72:73] op_sel_hi:[0,1]
	v_pk_mul_f32 v[70:71], v[0:1], v[30:31] op_sel_hi:[0,1]
	v_pk_mul_f32 v[14:15], v[70:71], v[60:61]
	v_pk_mul_f32 v[16:17], v[68:69], v[62:63]
	flat_store_dwordx4 v[6:7], v[14:17] offset:2048
	v_pk_mul_f32 v[68:69], v[0:1], v[74:75] op_sel_hi:[0,1]
	v_pk_mul_f32 v[70:71], v[0:1], v[34:35] op_sel_hi:[0,1]
	v_pk_mul_f32 v[14:15], v[70:71], v[64:65]
	v_pk_mul_f32 v[16:17], v[68:69], v[66:67]
	flat_store_dwordx4 v[6:7], v[14:17] offset:3072
	v_lshl_add_u64 v[6:7], v[6:7], 0, s[6:7]
	s_cmpk_gt_i32 s2, 0x7fff
	s_cbranch_scc1 .LBB0_29
	s_branch .LBB0_28
